# D1: attention K/V tiles staged by direct global->LDS DMA (per-lane source addresses reproduce swizzled images), one barrier per key tile, no VGPR staging; plus A2 mask rewrite
# speedup vs baseline: 1.0551x; 1.0440x over previous
; __device__ __forceinline__ int ltid() { int t = threadIdx.x; asm volatile("" : "+v"(t)); return t; }
; __device__ __forceinline__ int v_st(int k, int c) { const int kk = (k & ~0xC) | ((k & 4) << 1) | ((k & 8) >> 1); return ((kk >> 3) * 4 + (c >> 5)) * 512 + ((kk & 7) * 32 + (c & 31)) * 2; }
; #define A2_LOADT(t) do { const size_t ro_ = (size_t)((t) * 64 + sr) * D + sc; \
;         sk0 = att::load8(c.K + ro_); sk1 = att::load8(c.K + ro_ + 32 * D); sv00 = att::load8(c.V0 + ro_); sv01 = att::load8(c.V0 + ro_ + 32 * D); sv10 = att::load8(c.V1 + ro_); sv11 = att::load8(c.V1 + ro_ + 32 * D); } while (0)
; __device__ __forceinline__ void attn2_block(const Blk& c, char* lds) {
;     const int tid = ltid(), wid = __builtin_amdgcn_readfirstlane(tid >> 6), lane = tid & 63, r32 = lane & 31, hi = lane >> 5;
;     const int g = wid & 3;
;     const int NT = (c.P0 + 127) / 64 + 1;
;     const int sr = tid >> 4, sc = (tid & 15) * 8, kws = KSWZ(sr, sc * 2), vst0 = att::v_st(sr, sc), vst1 = att::v_st(32 + sr, sc);
;     bf16x8 sk0, sk1, sv00, sv01, sv10, sv11;
;     float* ALb = (float*)(lds + L_AL) + g * 64; unsigned* FLb = (unsigned*)(lds + L_FL) + g * 2; float* LBb = (float*)(lds + L_LB) + g * 32;
;     char* Pb = lds + L_P + g * 8192;
;     A2_LOADT(0);
;     if (wid < 4) {
.LBB0_540:
	v_mov_b32_e32 v2, v1
	s_and_b64 s[2:3], s[72:73], exec
	v_ashrrev_i32_e32 v210, 4, v2
	v_lshlrev_b32_e32 v10, 3, v2
	v_and_b32_e32 v222, 0x78, v10
	v_ashrrev_i32_e32 v211, 31, v210
	v_lshlrev_b32_e32 v11, 1, v222
	v_lshlrev_b64 v[212:213], 8, v[210:211]
	v_or_b32_e32 v4, v212, v11
	v_mov_b32_e32 v5, v213
	v_readfirstlane_b32 s2, v2
	v_and_b32_e32 v8, 3, v210
	v_lshlrev_b32_e32 v4, 8, v210
	v_and_b32_e32 v5, 0x70, v2
	v_bitop3_b32 v4, v11, v4, v5 bitop3:0xde
	v_and_b32_e32 v5, 0xfffff0, v210
	v_lshlrev_b32_e32 v6, 1, v210
	v_and_or_b32 v5, v6, 8, v5
	v_lshrrev_b32_e32 v6, 1, v210
	v_lshrrev_b32_e32 v5, 1, v5
	v_bfe_u32 v7, v10, 5, 2
	v_or_b32_e32 v5, v5, v7
	v_and_or_b32 v6, v6, 4, v8
	s_cselect_b32 s30, s52, s53
	s_ashr_i32 s2, s2, 6
	v_lshlrev_b32_e32 v5, 9, v5
	v_lshlrev_b32_e32 v6, 6, v6
	v_and_b32_e32 v8, 48, v11
	s_and_b32 s82, s2, 3
	v_or3_b32 v223, v5, v6, v8
	v_add_u32_e32 v5, 32, v210
	v_and_b32_e32 v9, 0xfffff0, v5
	v_lshlrev_b32_e32 v5, 1, v5
	s_lshl_b32 s3, s82, 8
	v_and_or_b32 v5, v5, 8, v9
	s_add_i32 s17, s3, 0
	s_lshl_b32 s3, s82, 3
	v_lshrrev_b32_e32 v5, 1, v5
	s_add_i32 s79, s3, 0
	s_lshl_b32 s3, s82, 7
	v_or_b32_e32 v5, v5, v7
	s_add_i32 s65, s3, 0
	s_lshl_b32 s3, s82, 13
	v_lshlrev_b32_e32 v5, 9, v5
	s_add_i32 s16, s3, 0
	v_and_b32_e32 v225, 63, v2
	v_and_b32_e32 v211, 31, v2
	v_bfe_u32 v226, v2, 5, 1
	s_lshr_b32 s78, s30, 6
	v_or3_b32 v224, v5, v6, v8
	s_add_i32 s17, s17, 0x20000
	s_add_i32 s79, s79, 0x20400
	s_add_i32 s65, s65, 0x20480
	s_add_i32 s16, s16, 0x18000
	v_and_b32_e32 v2, 15, v2
	v_lshlrev_b32_e32 v216, 4, v226
	v_add_u32_e32 v229, 0, v4
	v_add_u32_e32 v227, 0, v223
	v_add_u32_e32 v228, 0, v224
	v_lshl_or_b32 v214, v2, 4, v212
	s_lshl_b32 s100, s2, 11
	v_lshrrev_b32_e32 v4, 6, v1
	v_bfe_u32 v5, v1, 4, 2
	v_lshl_or_b32 v4, v4, 3, v5
	v_and_b32_e32 v6, 15, v1
	v_xor_b32_e32 v6, v6, v5
	v_lshlrev_b32_e32 v6, 4, v6
	v_lshl_or_b32 v4, v4, 8, v6
	v_mov_b32_e32 v5, 0
	v_xor_b32_e32 v6, 64, v4
	v_mov_b32_e32 v7, 0
	v_lshl_add_u64 v[164:165], s[0:1], 0, v[4:5]
	v_lshl_add_u64 v[166:167], s[0:1], 0, v[6:7]
	v_bfe_u32 v4, v1, 7, 2
	v_bfe_u32 v6, v1, 4, 1
	v_lshl_or_b32 v4, v4, 1, v6
	v_bfe_u32 v6, v1, 6, 1
	v_lshl_or_b32 v4, v4, 1, v6
	v_bfe_u32 v6, v1, 2, 2
	v_lshl_or_b32 v4, v4, 2, v6
	v_bfe_u32 v6, v1, 5, 1
	v_and_b32_e32 v8, 3, v1
	v_lshl_or_b32 v6, v6, 2, v8
	v_lshlrev_b32_e32 v6, 4, v6
	v_lshl_or_b32 v4, v4, 8, v6
	v_lshl_add_u64 v[168:169], s[6:7], 0, v[4:5]
	v_lshl_add_u64 v[170:171], s[8:9], 0, v[4:5]
	s_add_i32 m0, s100, 0x10000
	s_mov_b64 s[10:11], 0x4000
	global_load_lds_dwordx4 v[164:165], off
	global_load_lds_dwordx4 v[166:167], off offset:1024
	v_lshl_add_u64 v[164:165], v[164:165], 0, s[10:11]
	v_lshl_add_u64 v[166:167], v[166:167], 0, s[10:11]
	s_cmp_gt_i32 s2, 3
	s_mov_b64 s[2:3], -1
	s_cbranch_scc1 .LBB0_542
	s_and_b64 vcc, exec, s[2:3]
	s_cbranch_vccz .LBB0_539
	s_branch .LBB0_551
; #define SBAR() __builtin_amdgcn_sched_barrier(0)
; __device__ __forceinline__ int v_rd_base(int lane) { return ((lane & 3) << 3) | (((lane >> 2) & 3) << 6) | (((lane >> 4) & 1) << 5) | (((lane >> 5) & 1) << 8); }
; __device__ __forceinline__ int crow(int r, int hi) { return (r & 3) + 8 * (r >> 2) + 4 * hi; }
; #define A2_LOADT(t) do { const size_t ro_ = (size_t)((t) * 64 + sr) * D + sc; \
;         sk0 = att::load8(c.K + ro_); sk1 = att::load8(c.K + ro_ + 32 * D); sv00 = att::load8(c.V0 + ro_); sv01 = att::load8(c.V0 + ro_ + 32 * D); sv10 = att::load8(c.V1 + ro_); sv11 = att::load8(c.V1 + ro_ + 32 * D); } while (0)
; __device__ __forceinline__ void attn2_block(const Blk& c, char* lds) {
;     ...
;     } else {
;         asm volatile("s_waitcnt vmcnt(0)" ::: "memory"); A2_WRITET(0); __syncthreads();
;         f32x16 o[8];
; #pragma unroll
;         for (int d_ = 0; d_ < 8; ++d_) o[d_] = f32x16{};
;         const int vbase = (int)(uintptr_t)(lds + L_V) + att::v_rd_base(lane);
;         for (int s = 0; s <= NT; ++s) {
;             if (s + 1 < NT) A2_LOADT(s + 1);
;             SBAR();
;             if (s >= 1) {
;                 const int par = (s - 1) & 1;
;                 const unsigned fl = (unsigned)__builtin_amdgcn_readfirstlane((int)FLb[par]);
;                 if (fl) {
; #pragma unroll
;                     for (int r = 0; r < 16; ++r) { const float a = ALb[par * 32 + att::crow(r, hi)];
; #pragma unroll
;                         for (int d_ = 0; d_ < 8; ++d_) o[d_][r] *= a; } }
;                 const char* pr = Pb + par * 4096 + lane * 16;
;                 const bf16x8 pa0 = *(const bf16x8*)(pr), pa1 = *(const bf16x8*)(pr + 1024), pa2 = *(const bf16x8*)(pr + 2048), pa3 = *(const bf16x8*)(pr + 3072);
;                 const int vb = vbase + par * 2 * SHM_V;
;                 att::pv_tile<0>(o, vb, pa0, pa1, pa2, pa3);
;                 att::pv_tile<0>(o + 4, vb + SHM_V, pa0, pa1, pa2, pa3);
;             }
;             __syncthreads();
;             if (s + 1 < NT) { asm volatile("s_waitcnt vmcnt(0)" ::: "memory"); A2_WRITET((s + 1) & 1); }
;             __syncthreads();
.LBB0_542:
	v_lshlrev_b32_e32 v4, 3, v225
	v_lshlrev_b32_e32 v2, 4, v225
	v_lshlrev_b32_e32 v5, 1, v225
	v_and_b32_e32 v4, 0x118, v4
	s_cmp_lg_u32 0, -1
	v_add_u32_e32 v230, s16, v2
	v_and_b32_e32 v2, 0xc0, v2
	v_and_or_b32 v4, v5, 32, v4
	s_cselect_b32 s2, 0, 0
	v_add3_u32 v231, v2, s2, v4
	v_lshl_or_b32 v212, v222, 1, v212
	s_waitcnt vmcnt(0)
	s_barrier
	s_add_i32 m0, s100, 0x14000
	s_mov_b64 s[10:11], 0x4000
	global_load_lds_dwordx4 v[164:165], off
	global_load_lds_dwordx4 v[166:167], off offset:1024
	s_mov_b32 m0, s100
	v_lshl_add_u64 v[164:165], v[164:165], 0, s[10:11]
	global_load_lds_dwordx4 v[168:169], off
	s_add_i32 m0, s100, 0x380
	v_lshl_add_u64 v[166:167], v[166:167], 0, s[10:11]
	global_load_lds_dwordx4 v[168:169], off offset:128
	s_add_i32 m0, s100, 0x4000
	v_lshl_add_u64 v[168:169], v[168:169], 0, s[10:11]
	global_load_lds_dwordx4 v[170:171], off
	s_add_i32 m0, s100, 0x4380
	s_nop 0
	global_load_lds_dwordx4 v[170:171], off offset:128
	v_lshl_add_u64 v[170:171], v[170:171], 0, s[10:11]
	v_mov_b32_e32 v16, v3
	v_mov_b32_e32 v17, v3
	s_lshl_b32 s2, s30, 8
	v_mov_b32_e32 v2, v3
	v_mov_b32_e32 v4, v3
	v_mov_b32_e32 v5, v3
	v_mov_b32_e32 v6, v3
	v_mov_b32_e32 v7, v3
	v_mov_b32_e32 v8, v3
	v_mov_b32_e32 v9, v3
	v_mov_b32_e32 v10, v3
	v_mov_b32_e32 v11, v3
	v_mov_b32_e32 v12, v3
	v_mov_b32_e32 v13, v3
	v_mov_b32_e32 v14, v3
	v_mov_b32_e32 v15, v3
	v_mov_b64_e32 v[130:131], v[16:17]
	v_mov_b64_e32 v[114:115], v[16:17]
	v_mov_b64_e32 v[98:99], v[16:17]
	v_mov_b64_e32 v[82:83], v[16:17]
	v_mov_b64_e32 v[66:67], v[16:17]
	v_mov_b64_e32 v[50:51], v[16:17]
	v_mov_b64_e32 v[34:35], v[16:17]
	s_and_b32 s2, s2, 0x1fc000
	v_mov_b32_e32 v215, v213
	v_mov_b64_e32 v[128:129], v[14:15]
	v_mov_b64_e32 v[126:127], v[12:13]
	v_mov_b64_e32 v[124:125], v[10:11]
	v_mov_b64_e32 v[122:123], v[8:9]
	v_mov_b64_e32 v[120:121], v[6:7]
	v_mov_b64_e32 v[118:119], v[4:5]
	v_mov_b64_e32 v[116:117], v[2:3]
	v_mov_b64_e32 v[112:113], v[14:15]
	v_mov_b64_e32 v[110:111], v[12:13]
	v_mov_b64_e32 v[108:109], v[10:11]
	v_mov_b64_e32 v[106:107], v[8:9]
	v_mov_b64_e32 v[104:105], v[6:7]
	v_mov_b64_e32 v[102:103], v[4:5]
	v_mov_b64_e32 v[100:101], v[2:3]
	v_mov_b64_e32 v[96:97], v[14:15]
	v_mov_b64_e32 v[94:95], v[12:13]
	v_mov_b64_e32 v[92:93], v[10:11]
	v_mov_b64_e32 v[90:91], v[8:9]
	v_mov_b64_e32 v[88:89], v[6:7]
	v_mov_b64_e32 v[86:87], v[4:5]
	v_mov_b64_e32 v[84:85], v[2:3]
	v_mov_b64_e32 v[80:81], v[14:15]
	v_mov_b64_e32 v[78:79], v[12:13]
	v_mov_b64_e32 v[76:77], v[10:11]
	v_mov_b64_e32 v[74:75], v[8:9]
	v_mov_b64_e32 v[72:73], v[6:7]
	v_mov_b64_e32 v[70:71], v[4:5]
	v_mov_b64_e32 v[68:69], v[2:3]
	v_mov_b64_e32 v[64:65], v[14:15]
	v_mov_b64_e32 v[62:63], v[12:13]
	v_mov_b64_e32 v[60:61], v[10:11]
	v_mov_b64_e32 v[58:59], v[8:9]
	v_mov_b64_e32 v[56:57], v[6:7]
	v_mov_b64_e32 v[54:55], v[4:5]
	v_mov_b64_e32 v[52:53], v[2:3]
	v_mov_b64_e32 v[48:49], v[14:15]
	v_mov_b64_e32 v[46:47], v[12:13]
	v_mov_b64_e32 v[44:45], v[10:11]
	v_mov_b64_e32 v[42:43], v[8:9]
	v_mov_b64_e32 v[40:41], v[6:7]
	v_mov_b64_e32 v[38:39], v[4:5]
	v_mov_b64_e32 v[36:37], v[2:3]
	v_mov_b64_e32 v[32:33], v[14:15]
	v_mov_b64_e32 v[30:31], v[12:13]
	v_mov_b64_e32 v[28:29], v[10:11]
	v_mov_b64_e32 v[26:27], v[8:9]
	v_mov_b64_e32 v[24:25], v[6:7]
	v_mov_b64_e32 v[22:23], v[4:5]
	v_mov_b64_e32 v[20:21], v[2:3]
	v_mov_b64_e32 v[18:19], v[16:17]
	v_add_u32_e32 v212, s17, v216
	s_add_u32 s83, s2, 0x8000
	v_lshl_add_u64 v[218:219], s[46:47], 0, v[214:215]
	v_lshl_add_u64 v[220:221], s[58:59], 0, v[214:215]
	s_mov_b32 s84, 2
	s_mov_b64 s[2:3], 0
	v_mov_b64_e32 v[16:17], v[14:15]
	v_mov_b64_e32 v[14:15], v[12:13]
	v_mov_b64_e32 v[12:13], v[10:11]
	v_mov_b64_e32 v[10:11], v[8:9]
	v_mov_b64_e32 v[8:9], v[6:7]
	v_mov_b64_e32 v[6:7], v[4:5]
	v_mov_b64_e32 v[4:5], v[2:3]
	s_waitcnt vmcnt(0)
	s_waitcnt lgkmcnt(0)
	s_barrier
	s_branch .LBB0_544
.LBB0_543:
	s_add_i32 s84, s84, 1
	s_add_u32 s2, s2, 0x4000
	s_addc_u32 s3, s3, 0
	s_cmp_eq_u32 s83, s2
	s_cbranch_scc1 .LBB0_550
.LBB0_544:
	s_add_i32 s85, s84, -1
	s_add_i32 s10, s78, 1
	s_cmp_gt_u32 s85, s10
	s_cbranch_scc1 .LBB0_546
	s_and_b32 s10, s85, 1
	s_lshl_b32 s10, s10, 15
	s_add_i32 s10, s10, s100
	s_mov_b32 m0, s10
	v_lshl_add_u64 v[172:173], v[168:169], 0, s[2:3]
	global_load_lds_dwordx4 v[172:173], off
	s_add_i32 m0, s10, 0x380
	v_lshl_add_u64 v[174:175], v[170:171], 0, s[2:3]
	global_load_lds_dwordx4 v[172:173], off offset:128
	s_add_i32 m0, s10, 0x4000
	s_nop 0
	global_load_lds_dwordx4 v[174:175], off
	s_add_i32 m0, s10, 0x4380
	s_cmp_gt_u32 s85, s78
	global_load_lds_dwordx4 v[174:175], off offset:128
	s_cbranch_scc1 .LBB0_546
	s_andn2_b32 s10, 1, s85
	s_lshl_b32 s10, s10, 14
	s_add_i32 s10, s10, s100
	s_add_i32 m0, s10, 0x10000
	v_lshl_add_u64 v[172:173], v[164:165], 0, s[2:3]
	global_load_lds_dwordx4 v[172:173], off
	v_lshl_add_u64 v[174:175], v[166:167], 0, s[2:3]
	s_nop 0
	global_load_lds_dwordx4 v[174:175], off offset:1024

; #define A2_WRITET(buf) do { char* kd_ = lds + L_K + (buf) * SHM_K; char* vd_ = lds + L_V + (buf) * 2 * SHM_V; \
;         *(bf16x8*)(kd_ + kws) = sk0; *(bf16x8*)(kd_ + kws + 32 * 256) = sk1; *(bf16x8*)(vd_ + vst0) = sv00; *(bf16x8*)(vd_ + vst1) = sv01; *(bf16x8*)(vd_ + SHM_V + vst0) = sv10; *(bf16x8*)(vd_ + SHM_V + vst1) = sv11; } while (0)
; template <int VB>
; __device__ __forceinline__ void pv_tile(f32x16* o, int vb0, bf16x8 pa0, bf16x8 pa1, bf16x8 pa2, bf16x8 pa3) {
;     ...
;     PV_D0(0); PV_D0(1); PV_D0(2); PV_D0(3);
; __device__ __forceinline__ void attn2_block(const Blk& c, char* lds) {
;     ...
;                 const char* pr = Pb + par * 4096 + lane * 16;
;                 const bf16x8 pa0 = *(const bf16x8*)(pr), pa1 = *(const bf16x8*)(pr + 1024), pa2 = *(const bf16x8*)(pr + 2048), pa3 = *(const bf16x8*)(pr + 3072);
;                 const int vb = vbase + par * 2 * SHM_V;
;                 att::pv_tile<0>(o, vb, pa0, pa1, pa2, pa3);
;                 att::pv_tile<0>(o + 4, vb + SHM_V, pa0, pa1, pa2, pa3);
;             }
;             __syncthreads();
;             if (s + 1 < NT) { asm volatile("s_waitcnt vmcnt(0)" ::: "memory"); A2_WRITET((s + 1) & 1); }
;             __syncthreads();
.LBB0_548:
	v_lshl_add_u32 v2, s85, 12, v230
	ds_read_b128 v[192:195], v2
	ds_read_b128 v[188:191], v2 offset:1024
	ds_read_b128 v[184:187], v2 offset:2048
	ds_read_b128 v[180:183], v2 offset:3072
	v_lshl_add_u32 v2, s85, 15, v231
	ds_read_b64_tr_b16 v[232:233], v2 offset:0
	ds_read_b64_tr_b16 v[234:235], v2 offset:0x800
	ds_read_b64_tr_b16 v[242:243], v2 offset:0x1000
	ds_read_b64_tr_b16 v[244:245], v2 offset:0x1800
	ds_read_b64_tr_b16 v[246:247], v2 offset:0x2000
	ds_read_b64_tr_b16 v[248:249], v2 offset:0x2800
	ds_read_b64_tr_b16 v[250:251], v2 offset:0x3000
	ds_read_b64_tr_b16 v[252:253], v2 offset:0x3800
	s_waitcnt lgkmcnt(0)
	s_waitcnt lgkmcnt(3)
	v_mfma_f32_32x32x16_bf16 v[116:131], v[192:195], v[232:235], v[116:131]
	ds_read_b64_tr_b16 v[232:233], v2 offset:0x200
	ds_read_b64_tr_b16 v[234:235], v2 offset:0xa00
	s_waitcnt lgkmcnt(2)
	v_mfma_f32_32x32x16_bf16 v[116:131], v[188:191], v[242:245], v[116:131]
	ds_read_b64_tr_b16 v[242:243], v2 offset:0x1200
	ds_read_b64_tr_b16 v[244:245], v2 offset:0x1a00
	s_waitcnt lgkmcnt(1)
	v_mfma_f32_32x32x16_bf16 v[116:131], v[184:187], v[246:249], v[116:131]
	ds_read_b64_tr_b16 v[246:247], v2 offset:0x2200
	ds_read_b64_tr_b16 v[248:249], v2 offset:0x2a00
	s_waitcnt lgkmcnt(0)
	v_mfma_f32_32x32x16_bf16 v[116:131], v[180:183], v[250:253], v[116:131]
	ds_read_b64_tr_b16 v[250:251], v2 offset:0x3200
	ds_read_b64_tr_b16 v[252:253], v2 offset:0x3a00
	s_waitcnt lgkmcnt(0)
	v_mfma_f32_32x32x16_bf16 v[100:115], v[192:195], v[232:235], v[100:115]
	ds_read_b64_tr_b16 v[232:233], v2 offset:0x400
	ds_read_b64_tr_b16 v[234:235], v2 offset:0xc00
	v_mfma_f32_32x32x16_bf16 v[100:115], v[188:191], v[242:245], v[100:115]
	ds_read_b64_tr_b16 v[242:243], v2 offset:0x1400
	ds_read_b64_tr_b16 v[244:245], v2 offset:0x1c00
	v_mfma_f32_32x32x16_bf16 v[100:115], v[184:187], v[246:249], v[100:115]
	ds_read_b64_tr_b16 v[246:247], v2 offset:0x2400
	ds_read_b64_tr_b16 v[248:249], v2 offset:0x2c00
	v_mfma_f32_32x32x16_bf16 v[100:115], v[180:183], v[250:253], v[100:115]
	ds_read_b64_tr_b16 v[250:251], v2 offset:0x3400
	ds_read_b64_tr_b16 v[252:253], v2 offset:0x3c00
	s_waitcnt lgkmcnt(0)
	v_mfma_f32_32x32x16_bf16 v[84:99], v[192:195], v[232:235], v[84:99]
	ds_read_b64_tr_b16 v[232:233], v2 offset:0x600
	ds_read_b64_tr_b16 v[234:235], v2 offset:0xe00
	v_mfma_f32_32x32x16_bf16 v[84:99], v[188:191], v[242:245], v[84:99]
	ds_read_b64_tr_b16 v[242:243], v2 offset:0x1600
	ds_read_b64_tr_b16 v[244:245], v2 offset:0x1e00
	v_mfma_f32_32x32x16_bf16 v[84:99], v[184:187], v[246:249], v[84:99]
	ds_read_b64_tr_b16 v[246:247], v2 offset:0x2600
	ds_read_b64_tr_b16 v[248:249], v2 offset:0x2e00
	v_mfma_f32_32x32x16_bf16 v[84:99], v[180:183], v[250:253], v[84:99]
	ds_read_b64_tr_b16 v[250:251], v2 offset:0x3600
	ds_read_b64_tr_b16 v[252:253], v2 offset:0x3e00
	s_waitcnt lgkmcnt(0)
	v_mfma_f32_32x32x16_bf16 v[68:83], v[192:195], v[232:235], v[68:83]
	v_add_u32_e32 v2, 0x4000, v2
	ds_read_b64_tr_b16 v[232:233], v2 offset:0
	ds_read_b64_tr_b16 v[234:235], v2 offset:0x800
	v_mfma_f32_32x32x16_bf16 v[68:83], v[188:191], v[242:245], v[68:83]
	ds_read_b64_tr_b16 v[242:243], v2 offset:0x1000
	ds_read_b64_tr_b16 v[244:245], v2 offset:0x1800
	v_mfma_f32_32x32x16_bf16 v[68:83], v[184:187], v[246:249], v[68:83]
	ds_read_b64_tr_b16 v[246:247], v2 offset:0x2000
	ds_read_b64_tr_b16 v[248:249], v2 offset:0x2800
	v_mfma_f32_32x32x16_bf16 v[68:83], v[180:183], v[250:253], v[68:83]
	ds_read_b64_tr_b16 v[250:251], v2 offset:0x3000
	ds_read_b64_tr_b16 v[252:253], v2 offset:0x3800
	s_waitcnt lgkmcnt(0)
	v_mfma_f32_32x32x16_bf16 v[52:67], v[192:195], v[232:235], v[52:67]
	ds_read_b64_tr_b16 v[232:233], v2 offset:0x200
	ds_read_b64_tr_b16 v[234:235], v2 offset:0xa00
	v_mfma_f32_32x32x16_bf16 v[52:67], v[188:191], v[242:245], v[52:67]
	ds_read_b64_tr_b16 v[242:243], v2 offset:0x1200
	ds_read_b64_tr_b16 v[244:245], v2 offset:0x1a00
	v_mfma_f32_32x32x16_bf16 v[52:67], v[184:187], v[246:249], v[52:67]
	ds_read_b64_tr_b16 v[246:247], v2 offset:0x2200
	ds_read_b64_tr_b16 v[248:249], v2 offset:0x2a00
	v_mfma_f32_32x32x16_bf16 v[52:67], v[180:183], v[250:253], v[52:67]
	ds_read_b64_tr_b16 v[250:251], v2 offset:0x3200
	ds_read_b64_tr_b16 v[252:253], v2 offset:0x3a00
	s_waitcnt lgkmcnt(0)
	v_mfma_f32_32x32x16_bf16 v[36:51], v[192:195], v[232:235], v[36:51]
	ds_read_b64_tr_b16 v[232:233], v2 offset:0x400
	ds_read_b64_tr_b16 v[234:235], v2 offset:0xc00
	v_mfma_f32_32x32x16_bf16 v[36:51], v[188:191], v[242:245], v[36:51]
	ds_read_b64_tr_b16 v[242:243], v2 offset:0x1400
	ds_read_b64_tr_b16 v[244:245], v2 offset:0x1c00
	v_mfma_f32_32x32x16_bf16 v[36:51], v[184:187], v[246:249], v[36:51]
	ds_read_b64_tr_b16 v[246:247], v2 offset:0x2400
	ds_read_b64_tr_b16 v[248:249], v2 offset:0x2c00
	v_mfma_f32_32x32x16_bf16 v[36:51], v[180:183], v[250:253], v[36:51]
	ds_read_b64_tr_b16 v[250:251], v2 offset:0x3400
	ds_read_b64_tr_b16 v[252:253], v2 offset:0x3c00
	s_waitcnt lgkmcnt(0)
	v_mfma_f32_32x32x16_bf16 v[20:35], v[192:195], v[232:235], v[20:35]
	ds_read_b64_tr_b16 v[232:233], v2 offset:0x600
	ds_read_b64_tr_b16 v[234:235], v2 offset:0xe00
	v_mfma_f32_32x32x16_bf16 v[20:35], v[188:191], v[242:245], v[20:35]
	ds_read_b64_tr_b16 v[242:243], v2 offset:0x1600
	ds_read_b64_tr_b16 v[244:245], v2 offset:0x1e00
	v_mfma_f32_32x32x16_bf16 v[20:35], v[184:187], v[246:249], v[20:35]
	ds_read_b64_tr_b16 v[246:247], v2 offset:0x2600
	ds_read_b64_tr_b16 v[248:249], v2 offset:0x2e00
	v_mfma_f32_32x32x16_bf16 v[20:35], v[180:183], v[250:253], v[20:35]
	ds_read_b64_tr_b16 v[250:251], v2 offset:0x3600
	ds_read_b64_tr_b16 v[252:253], v2 offset:0x3e00
	s_waitcnt lgkmcnt(0)
	v_mfma_f32_32x32x16_bf16 v[4:19], v[192:195], v[232:235], v[4:19]
	s_waitcnt vmcnt(0)
	s_barrier
	v_mfma_f32_32x32x16_bf16 v[4:19], v[188:191], v[242:245], v[4:19]
	v_mfma_f32_32x32x16_bf16 v[4:19], v[184:187], v[246:249], v[4:19]
	v_mfma_f32_32x32x16_bf16 v[4:19], v[180:183], v[250:253], v[4:19]
	s_branch .LBB0_543

; #define SBAR() __builtin_amdgcn_sched_barrier(0)
; #define A2_LOADT(t) do { const size_t ro_ = (size_t)((t) * 64 + sr) * D + sc; \
;         sk0 = att::load8(c.K + ro_); sk1 = att::load8(c.K + ro_ + 32 * D); sv00 = att::load8(c.V0 + ro_); sv01 = att::load8(c.V0 + ro_ + 32 * D); sv10 = att::load8(c.V1 + ro_); sv11 = att::load8(c.V1 + ro_ + 32 * D); } while (0)
; #define A2_WRITET(buf) do { char* kd_ = lds + L_K + (buf) * SHM_K; char* vd_ = lds + L_V + (buf) * 2 * SHM_V; \
;         *(bf16x8*)(kd_ + kws) = sk0; *(bf16x8*)(kd_ + kws + 32 * 256) = sk1; *(bf16x8*)(vd_ + vst0) = sv00; *(bf16x8*)(vd_ + vst1) = sv01; *(bf16x8*)(vd_ + SHM_V + vst0) = sv10; *(bf16x8*)(vd_ + SHM_V + vst1) = sv11; } while (0)
; __device__ __forceinline__ void qkt_rt(f32x16& p0, f32x16& p1, const char* Kb, int r32, int hi, const bf16x8* qr) {
;     p0 = f32x16{}; p1 = f32x16{};
;     const char* kb[4];
; #pragma unroll
;     for (int dd = 0; dd < 4; ++dd) kb[dd] = Kb + KSWZ(r32, (dd * 16 + hi * 8) * 2);
; #pragma unroll
;     for (int d0 = 0; d0 < 8; ++d0) { const char* a = kb[d0 & 3] + (d0 >> 2) * 128;
;         bf16x8 b0 = *reinterpret_cast<const bf16x8*>(a);
;         bf16x8 b1 = *reinterpret_cast<const bf16x8*>(a + 32 * 256);
;         p0 = __builtin_amdgcn_mfma_f32_32x32x16_bf16(b0, qr[d0], p0, 0, 0, 0);
;         p1 = __builtin_amdgcn_mfma_f32_32x32x16_bf16(b1, qr[d0], p1, 0, 0, 0); }
; }
; __device__ __forceinline__ void attn2_block(const Blk& c, char* lds) {
;     ...
;     if (wid < 4) {
;         bf16x8 qr[8];
; #pragma unroll
;         for (int d0 = 0; d0 < 8; ++d0) qr[d0] = att::load8(c.Q + (size_t)(g * 32 + r32) * D + d0 * 16 + hi * 8);
;         asm volatile("s_waitcnt vmcnt(0)" ::: "memory"); A2_WRITET(0); __syncthreads();
;         const int qlo = c.P0 + g * 32, qm = qlo + r32 - 4 * hi;
;         const float* bt = (const float*)(lds + L_BT) + c.hm * 256;
;         float m_reg = -1e30f, l_reg = 0.f;
;         for (int s = 0; s <= NT; ++s) {
;             const int par = s & 1;
;             if (s + 1 < NT) A2_LOADT(s + 1);
;             SBAR();
;             if (s < NT) {
;                 f32x16 p0, p1; float mn, al; bf16x8 pa0, pa1, pa2, pa3;
;                 qkt_rt(p0, p1, lds + L_K + par * SHM_K, r32, hi, qr);
.LBB0_551:
	s_or_b64 s[2:3], s[14:15], s[30:31]
	s_lshl_b32 s10, s82, 5
	s_lshl_b64 s[2:3], s[2:3], 8
	s_add_u32 s2, s27, s2
	v_or_b32_e32 v2, s10, v211
	s_addc_u32 s3, s34, s3
	v_lshlrev_b32_e32 v2, 8, v2
	v_lshl_add_u64 v[4:5], s[2:3], 0, v[2:3]
	v_mov_b32_e32 v217, v3
	v_lshl_add_u64 v[4:5], v[4:5], 0, v[216:217]
	global_load_dwordx4 v[104:107], v[4:5], off
	global_load_dwordx4 v[100:103], v[4:5], off offset:32
	global_load_dwordx4 v[96:99], v[4:5], off offset:64
	global_load_dwordx4 v[92:95], v[4:5], off offset:96
	global_load_dwordx4 v[88:91], v[4:5], off offset:128
	global_load_dwordx4 v[84:87], v[4:5], off offset:160
	global_load_dwordx4 v[80:83], v[4:5], off offset:192
	global_load_dwordx4 v[76:79], v[4:5], off offset:224
	s_or_b32 s85, s10, s30
	s_add_i32 s10, s30, s10
	s_waitcnt vmcnt(0)
	v_lshlrev_b32_e32 v4, 4, v211
	s_movk_i32 s2, 0x70
	s_lshl_b32 s11, s30, 8
	s_sub_i32 s10, s10, 27
	v_and_b32_e32 v5, 0x70, v4
	v_bitop3_b32 v121, v216, v4, s2 bitop3:0x78
	s_movk_i32 s2, 0x60
	v_lshlrev_b32_e32 v114, 2, v226
	s_and_b32 s11, s11, 0x1fc000
	v_add_u32_e32 v4, s10, v211
	v_mov_b32_e32 v215, v213
	v_add_u32_e32 v116, 0x10000, v229
	v_lshl_add_u32 v2, v211, 2, s17
	v_lshlrev_b32_e32 v119, 8, v211
	v_bitop3_b32 v122, v216, v5, 32 bitop3:0x36
	v_bitop3_b32 v123, v216, v5, 64 bitop3:0x36
	v_bitop3_b32 v124, v216, v5, s2 bitop3:0x36
	s_add_i32 s86, s85, 0xffffff80
	v_lshl_add_u32 v112, v225, 4, s16
	v_cmp_gt_u32_e64 s[2:3], 32, v225
	s_mov_b32 s84, 0
	v_cmp_eq_u32_e64 s[4:5], 0, v225
	s_add_u32 s87, s11, 0x4000
	v_sub_u32_e32 v125, v4, v114
	v_lshl_add_u64 v[108:109], s[46:47], 0, v[214:215]
	v_lshl_add_u64 v[110:111], s[58:59], 0, v[214:215]
	v_mov_b32_e32 v117, 0
	v_mov_b32_e32 v113, 0xf149f2ca
	s_mov_b64 s[82:83], 0
	s_mov_b32 s30, 0
	s_waitcnt lgkmcnt(0)
	s_barrier
.LBB0_552:
	s_and_b32 s88, s30, 1
	s_lshl_b32 s10, s88, 15
	s_add_i32 s10, s10, s100
	s_mov_b32 m0, s10
	v_lshl_add_u64 v[52:53], v[168:169], 0, s[82:83]
	global_load_lds_dwordx4 v[52:53], off
	s_add_i32 m0, s10, 0x380
	v_lshl_add_u64 v[54:55], v[170:171], 0, s[82:83]
	global_load_lds_dwordx4 v[52:53], off offset:128
	s_add_i32 m0, s10, 0x4000
	s_nop 0
	global_load_lds_dwordx4 v[54:55], off
	s_add_i32 m0, s10, 0x4380
	s_nop 0
	global_load_lds_dwordx4 v[54:55], off offset:128
	s_xor_b32 s10, s88, 1
	s_lshl_b32 s10, s10, 14
	s_add_i32 s10, s10, s100
	s_add_i32 m0, s10, 0x10000
	v_lshl_add_u64 v[56:57], v[164:165], 0, s[82:83]
	v_lshl_add_u64 v[58:59], v[166:167], 0, s[82:83]
	global_load_lds_dwordx4 v[56:57], off
	global_load_lds_dwordx4 v[58:59], off offset:1024
	s_lshl_b32 s10, s88, 14
	s_add_i32 s10, s10, 0
	s_add_i32 s10, s10, 0x10000
	v_add3_u32 v40, s10, v121, v119
	ds_read_b128 v[4:7], v40
	v_add3_u32 v41, s10, v122, v119
	ds_read_b128 v[36:39], v41
	v_add3_u32 v42, s10, v123, v119
	v_add3_u32 v43, s10, v124, v119
	s_add_i32 s10, s84, 63
	s_cmp_le_i32 s10, s86
	s_waitcnt vmcnt(13) lgkmcnt(1)
	v_mfma_f32_32x32x16_bf16 v[20:35], v[4:7], v[104:107], 0
	ds_read_b128 v[4:7], v40 offset:8192
	s_waitcnt vmcnt(12) lgkmcnt(1)
	v_mfma_f32_32x32x16_bf16 v[20:35], v[36:39], v[100:103], v[20:35]
	ds_read_b128 v[36:39], v41 offset:8192
	s_waitcnt lgkmcnt(1)
	v_mfma_f32_32x32x16_bf16 v[4:19], v[4:7], v[104:107], 0
	s_waitcnt lgkmcnt(0)
	v_mfma_f32_32x32x16_bf16 v[4:19], v[36:39], v[100:103], v[4:19]
	ds_read_b128 v[36:39], v42
	s_waitcnt vmcnt(11) lgkmcnt(0)
	v_mfma_f32_32x32x16_bf16 v[20:35], v[36:39], v[96:99], v[20:35]
	ds_read_b128 v[36:39], v42 offset:8192
	s_waitcnt lgkmcnt(0)
	v_mfma_f32_32x32x16_bf16 v[4:19], v[36:39], v[96:99], v[4:19]
	ds_read_b128 v[36:39], v43
	s_waitcnt vmcnt(10) lgkmcnt(0)
	v_mfma_f32_32x32x16_bf16 v[20:35], v[36:39], v[92:95], v[20:35]
	ds_read_b128 v[36:39], v43 offset:8192
	s_waitcnt lgkmcnt(0)
	v_mfma_f32_32x32x16_bf16 v[4:19], v[36:39], v[92:95], v[4:19]
	ds_read_b128 v[36:39], v40 offset:128
	s_waitcnt vmcnt(9) lgkmcnt(0)
	v_mfma_f32_32x32x16_bf16 v[20:35], v[36:39], v[88:91], v[20:35]
	ds_read_b128 v[36:39], v40 offset:8320
	s_waitcnt lgkmcnt(0)
	v_mfma_f32_32x32x16_bf16 v[4:19], v[36:39], v[88:91], v[4:19]
	ds_read_b128 v[36:39], v41 offset:128
	s_waitcnt vmcnt(8) lgkmcnt(0)
	v_mfma_f32_32x32x16_bf16 v[20:35], v[36:39], v[84:87], v[20:35]
	ds_read_b128 v[36:39], v41 offset:8320
	s_waitcnt lgkmcnt(0)
	v_mfma_f32_32x32x16_bf16 v[4:19], v[36:39], v[84:87], v[4:19]
	ds_read_b128 v[36:39], v42 offset:128
	s_waitcnt vmcnt(7) lgkmcnt(0)
	v_mfma_f32_32x32x16_bf16 v[20:35], v[36:39], v[80:83], v[20:35]
	ds_read_b128 v[36:39], v42 offset:8320
	s_waitcnt lgkmcnt(0)
	v_mfma_f32_32x32x16_bf16 v[4:19], v[36:39], v[80:83], v[4:19]
	ds_read_b128 v[36:39], v43 offset:128
	s_waitcnt vmcnt(6) lgkmcnt(0)
	v_mfma_f32_32x32x16_bf16 v[20:35], v[36:39], v[76:79], v[20:35]
	ds_read_b128 v[36:39], v43 offset:8320
	s_waitcnt lgkmcnt(0)
	v_mfma_f32_32x32x16_bf16 v[4:19], v[36:39], v[76:79], v[4:19]
	s_cbranch_scc1 .LBB0_586
; __device__ __forceinline__ void bias_mask_tile(f32x16& p0, f32x16& p1, int dq, const float* bt) {
;     const float NEG = -__builtin_inff();
; #pragma unroll
;     for (int r = 0; r < 16; ++r) {
;         const int c = (r & 3) + 8 * (r >> 2);
;         const int d0 = dq - c, d1 = dq - c - 32;
;         const unsigned i0 = (unsigned)d0 < 255u ? (unsigned)d0 : 255u, i1 = (unsigned)d1 < 255u ? (unsigned)d1 : 255u;
;         const float b0 = bt[i0], b1 = bt[i1];
;         p0[r] = d0 >= 0 ? p0[r] + b0 : NEG;
;         p1[r] = d1 >= 0 ? p1[r] + b1 : NEG;
;     }
; }
	v_add_u32_e32 v115, 27, v125
	v_lshl_add_u32 v36, v115, 2, s64
	v_add_u32_e32 v36, 0xffffff14, v36
	ds_read_b32 v132, v36 offset:236
	ds_read_b32 v133, v36 offset:232
	ds_read_b32 v134, v36 offset:228
	ds_read_b32 v135, v36 offset:224
	ds_read_b32 v136, v36 offset:204
	ds_read_b32 v137, v36 offset:200
	ds_read_b32 v138, v36 offset:196
	ds_read_b32 v139, v36 offset:192
	ds_read_b32 v140, v36 offset:172
	ds_read_b32 v141, v36 offset:168
	ds_read_b32 v142, v36 offset:164
	ds_read_b32 v143, v36 offset:160
	ds_read_b32 v144, v36 offset:140
	ds_read_b32 v145, v36 offset:136
	ds_read_b32 v146, v36 offset:132
	v_cmp_lt_i32_e32 vcc, -1, v115
	v_cmp_lt_i32_e64 s[16:17], 0, v115
	s_waitcnt lgkmcnt(14)
	v_add_f32_e32 v20, v20, v132
	ds_read_b32 v147, v36 offset:128
	s_waitcnt lgkmcnt(14)
	v_add_f32_e32 v21, v21, v133
	ds_read_b32 v148, v36 offset:108
	v_cndmask_b32_e32 v20, v240, v20, vcc
	v_cndmask_b32_e64 v21, v240, v21, s[16:17]
	v_cmp_lt_i32_e32 vcc, 1, v115
	v_cmp_lt_i32_e64 s[16:17], 2, v115
	s_waitcnt lgkmcnt(14)
	v_add_f32_e32 v22, v22, v134
	ds_read_b32 v149, v36 offset:104
	s_waitcnt lgkmcnt(14)
	v_add_f32_e32 v23, v23, v135
	ds_read_b32 v150, v36 offset:100
	v_cndmask_b32_e32 v22, v240, v22, vcc
	v_cndmask_b32_e64 v23, v240, v23, s[16:17]
	v_cmp_lt_i32_e32 vcc, 7, v115
	v_cmp_lt_i32_e64 s[16:17], 8, v115
	s_waitcnt lgkmcnt(14)
	v_add_f32_e32 v24, v24, v136
	ds_read_b32 v151, v36 offset:96
	s_waitcnt lgkmcnt(14)
	v_add_f32_e32 v25, v25, v137
	ds_read_b32 v152, v36 offset:76
	v_cndmask_b32_e32 v24, v240, v24, vcc
	v_cndmask_b32_e64 v25, v240, v25, s[16:17]
	v_cmp_lt_i32_e32 vcc, 9, v115
	v_cmp_lt_i32_e64 s[16:17], 10, v115
	s_waitcnt lgkmcnt(14)
	v_add_f32_e32 v26, v26, v138
	ds_read_b32 v153, v36 offset:72
	s_waitcnt lgkmcnt(14)
	v_add_f32_e32 v27, v27, v139
	ds_read_b32 v154, v36 offset:68
	v_cndmask_b32_e32 v26, v240, v26, vcc
	v_cndmask_b32_e64 v27, v240, v27, s[16:17]
	v_cmp_lt_i32_e32 vcc, 15, v115
	v_cmp_lt_i32_e64 s[16:17], 16, v115
	s_waitcnt lgkmcnt(14)
	v_add_f32_e32 v28, v28, v140
	ds_read_b32 v155, v36 offset:64
	s_waitcnt lgkmcnt(14)
	v_add_f32_e32 v29, v29, v141
	ds_read_b32 v60, v36 offset:44
	v_cndmask_b32_e32 v28, v240, v28, vcc
	v_cndmask_b32_e64 v29, v240, v29, s[16:17]
	v_cmp_lt_i32_e32 vcc, 17, v115
	v_cmp_lt_i32_e64 s[16:17], 18, v115
	s_waitcnt lgkmcnt(14)
	v_add_f32_e32 v30, v30, v142
	ds_read_b32 v61, v36 offset:40
	s_waitcnt lgkmcnt(14)
	v_add_f32_e32 v31, v31, v143
	ds_read_b32 v62, v36 offset:36
	v_cndmask_b32_e32 v30, v240, v30, vcc
	v_cndmask_b32_e64 v31, v240, v31, s[16:17]
	v_cmp_lt_i32_e32 vcc, 23, v115
	v_cmp_lt_i32_e64 s[16:17], 24, v115
	s_waitcnt lgkmcnt(14)
	v_add_f32_e32 v32, v32, v144
	ds_read_b32 v63, v36 offset:32
	s_waitcnt lgkmcnt(14)
	v_add_f32_e32 v33, v33, v145
	ds_read_b32 v64, v36 offset:12
	v_cndmask_b32_e32 v32, v240, v32, vcc
	v_cndmask_b32_e64 v33, v240, v33, s[16:17]
	v_cmp_lt_i32_e32 vcc, 25, v115
	v_cmp_lt_i32_e64 s[16:17], 26, v115
	s_waitcnt lgkmcnt(14)
	v_add_f32_e32 v34, v34, v146
	ds_read_b32 v65, v36 offset:8
	s_waitcnt lgkmcnt(14)
	v_add_f32_e32 v35, v35, v147
	ds_read_b32 v66, v36 offset:4
	v_cndmask_b32_e32 v34, v240, v34, vcc
	v_cndmask_b32_e64 v35, v240, v35, s[16:17]
	v_cmp_lt_i32_e32 vcc, 31, v115
	v_cmp_lt_i32_e64 s[16:17], 32, v115
	s_waitcnt lgkmcnt(14)
	v_add_f32_e32 v4, v4, v148
	ds_read_b32 v67, v36 offset:0
	s_waitcnt lgkmcnt(14)
	v_add_f32_e32 v5, v5, v149
	v_cndmask_b32_e32 v4, v240, v4, vcc
	v_cndmask_b32_e64 v5, v240, v5, s[16:17]
	v_cmp_lt_i32_e32 vcc, 33, v115
	v_cmp_lt_i32_e64 s[16:17], 34, v115
	s_waitcnt lgkmcnt(13)
	v_add_f32_e32 v6, v6, v150
	s_waitcnt lgkmcnt(12)
	v_add_f32_e32 v7, v7, v151
	v_cndmask_b32_e32 v6, v240, v6, vcc
	v_cndmask_b32_e64 v7, v240, v7, s[16:17]
	v_cmp_lt_i32_e32 vcc, 39, v115
	v_cmp_lt_i32_e64 s[16:17], 40, v115
	s_waitcnt lgkmcnt(11)
	v_add_f32_e32 v8, v8, v152
	s_waitcnt lgkmcnt(10)
	v_add_f32_e32 v9, v9, v153
	v_cndmask_b32_e32 v8, v240, v8, vcc
	v_cndmask_b32_e64 v9, v240, v9, s[16:17]
	v_cmp_lt_i32_e32 vcc, 41, v115
	v_cmp_lt_i32_e64 s[16:17], 42, v115
	s_waitcnt lgkmcnt(9)
	v_add_f32_e32 v10, v10, v154
	s_waitcnt lgkmcnt(8)
	v_add_f32_e32 v11, v11, v155
	v_cndmask_b32_e32 v10, v240, v10, vcc
	v_cndmask_b32_e64 v11, v240, v11, s[16:17]
	v_cmp_lt_i32_e32 vcc, 47, v115
	v_cmp_lt_i32_e64 s[16:17], 48, v115
	s_waitcnt lgkmcnt(7)
	v_add_f32_e32 v12, v12, v60
	s_waitcnt lgkmcnt(6)
	v_add_f32_e32 v13, v13, v61
	v_cndmask_b32_e32 v12, v240, v12, vcc
	v_cndmask_b32_e64 v13, v240, v13, s[16:17]
	v_cmp_lt_i32_e32 vcc, 49, v115
	v_cmp_lt_i32_e64 s[16:17], 50, v115
	s_waitcnt lgkmcnt(5)
	v_add_f32_e32 v14, v14, v62
	s_waitcnt lgkmcnt(4)
	v_add_f32_e32 v15, v15, v63
	v_cndmask_b32_e32 v14, v240, v14, vcc
	v_cndmask_b32_e64 v15, v240, v15, s[16:17]
	v_cmp_lt_i32_e32 vcc, 55, v115
	v_cmp_lt_i32_e64 s[16:17], 56, v115
	s_waitcnt lgkmcnt(3)
	v_add_f32_e32 v16, v16, v64
	s_waitcnt lgkmcnt(2)
	v_add_f32_e32 v17, v17, v65
	v_cndmask_b32_e32 v16, v240, v16, vcc
	v_cndmask_b32_e64 v17, v240, v17, s[16:17]
	v_cmp_lt_i32_e32 vcc, 57, v115
	v_cmp_lt_i32_e64 s[16:17], 58, v115
	s_waitcnt lgkmcnt(1)
	v_add_f32_e32 v18, v18, v66
	s_waitcnt lgkmcnt(0)
	v_add_f32_e32 v19, v19, v67
	v_cndmask_b32_e32 v18, v240, v18, vcc
	v_cndmask_b32_e64 v19, v240, v19, s[16:17]

; #define A2_WRITET(buf) do { char* kd_ = lds + L_K + (buf) * SHM_K; char* vd_ = lds + L_V + (buf) * 2 * SHM_V; \
;         *(bf16x8*)(kd_ + kws) = sk0; *(bf16x8*)(kd_ + kws + 32 * 256) = sk1; *(bf16x8*)(vd_ + vst0) = sv00; *(bf16x8*)(vd_ + vst1) = sv01; *(bf16x8*)(vd_ + SHM_V + vst0) = sv10; *(bf16x8*)(vd_ + SHM_V + vst1) = sv11; } while (0)
; __device__ __forceinline__ void qkt_rt(f32x16& p0, f32x16& p1, const char* Kb, int r32, int hi, const bf16x8* qr) {
;     p0 = f32x16{}; p1 = f32x16{};
;     const char* kb[4];
; #pragma unroll
;     for (int dd = 0; dd < 4; ++dd) kb[dd] = Kb + KSWZ(r32, (dd * 16 + hi * 8) * 2);
; #pragma unroll
;     for (int d0 = 0; d0 < 8; ++d0) { const char* a = kb[d0 & 3] + (d0 >> 2) * 128;
;         bf16x8 b0 = *reinterpret_cast<const bf16x8*>(a);
;         bf16x8 b1 = *reinterpret_cast<const bf16x8*>(a + 32 * 256);
;         p0 = __builtin_amdgcn_mfma_f32_32x32x16_bf16(b0, qr[d0], p0, 0, 0, 0);
;         p1 = __builtin_amdgcn_mfma_f32_32x32x16_bf16(b1, qr[d0], p1, 0, 0, 0); }
; }
; __device__ __forceinline__ void attn2_block(const Blk& c, char* lds) {
;     ...
;                 att::finishSM(p0, p1, al, l_reg, pa0, pa1, pa2, pa3);
;                 char* pw = Pb + par * 4096 + lane * 16;
;                 *(bf16x8*)(pw) = pa0; *(bf16x8*)(pw + 1024) = pa1; *(bf16x8*)(pw + 2048) = pa2; *(bf16x8*)(pw + 3072) = pa3;
;                 if (hi == 0) ALb[par * 32 + r32] = al;
;                 const bool resc = __any(al < 1.f);
;                 if (lane == 0) FLb[par] = resc ? 1u : 0u;
;             }
;             __syncthreads();
;             if (s + 1 < NT) { asm volatile("s_waitcnt vmcnt(0)" ::: "memory"); A2_WRITET((s + 1) & 1); }
;             __syncthreads();
.LBB0_590:
	s_or_b64 exec, exec, s[16:17]
	s_add_i32 s30, s30, 1
	s_and_b32 s88, s30, 1
	s_lshl_b32 s10, s88, 15
	s_lshl_b32 s16, s88, 14
	s_add_i32 s10, s10, 0
	s_waitcnt lgkmcnt(0)
	s_waitcnt vmcnt(0)
	s_barrier
	s_add_u32 s82, s82, 0x4000
	v_add_f32_e32 v115, v4, v5
	s_addc_u32 s83, s83, 0
	s_add_i32 s84, s84, 64
	v_fmac_f32_e32 v115, v117, v36
	s_cmp_eq_u32 s87, s82
	v_subrev_u32_e32 v125, 64, v125
	s_cbranch_scc1 .LBB0_592
	v_mov_b32_e32 v117, v115
	s_branch .LBB0_552
.LBB0_592:
	s_lshl_b32 s10, s88, 15
	s_add_i32 s10, s10, s100
	s_mov_b32 m0, s10
	v_lshl_add_u64 v[52:53], v[168:169], 0, s[82:83]
	global_load_lds_dwordx4 v[52:53], off
	s_add_i32 m0, s10, 0x380
	v_lshl_add_u64 v[54:55], v[170:171], 0, s[82:83]
	global_load_lds_dwordx4 v[52:53], off offset:128
	s_add_i32 m0, s10, 0x4000
	s_nop 0
	global_load_lds_dwordx4 v[54:55], off
	s_add_i32 m0, s10, 0x4380
	s_nop 0
	global_load_lds_dwordx4 v[54:55], off offset:128
	s_add_i32 s10, s16, 0
	s_add_i32 s10, s10, 0x10000
	v_add3_u32 v44, s10, v121, v119
	ds_read_b128 v[4:7], v44
	ds_read_b128 v[8:11], v44 offset:8192
	v_add3_u32 v45, s10, v122, v119
	ds_read_b128 v[36:39], v45
	ds_read_b128 v[40:43], v45 offset:8192
	v_add3_u32 v46, s10, v123, v119
	s_waitcnt lgkmcnt(3)
	v_mfma_f32_32x32x16_bf16 v[20:35], v[4:7], v[104:107], 0
	v_add3_u32 v47, s10, v124, v119
	s_or_b32 s10, s84, 63
	s_cmp_le_i32 s10, s86
	s_waitcnt lgkmcnt(2)
	v_mfma_f32_32x32x16_bf16 v[4:19], v[8:11], v[104:107], 0
	s_waitcnt lgkmcnt(1)
	v_mfma_f32_32x32x16_bf16 v[20:35], v[36:39], v[100:103], v[20:35]
	s_waitcnt lgkmcnt(0)
	v_mfma_f32_32x32x16_bf16 v[4:19], v[40:43], v[100:103], v[4:19]
	ds_read_b128 v[36:39], v46
	ds_read_b128 v[40:43], v46 offset:8192
	s_waitcnt lgkmcnt(1)
	v_mfma_f32_32x32x16_bf16 v[20:35], v[36:39], v[96:99], v[20:35]
	s_waitcnt lgkmcnt(0)
	v_mfma_f32_32x32x16_bf16 v[4:19], v[40:43], v[96:99], v[4:19]
	ds_read_b128 v[36:39], v47
	ds_read_b128 v[40:43], v47 offset:8192
	s_waitcnt lgkmcnt(1)
	v_mfma_f32_32x32x16_bf16 v[20:35], v[36:39], v[92:95], v[20:35]
	s_waitcnt lgkmcnt(0)
	v_mfma_f32_32x32x16_bf16 v[4:19], v[40:43], v[92:95], v[4:19]
	ds_read_b128 v[36:39], v44 offset:128
	ds_read_b128 v[40:43], v44 offset:8320
	s_waitcnt lgkmcnt(1)
	v_mfma_f32_32x32x16_bf16 v[20:35], v[36:39], v[88:91], v[20:35]
	s_waitcnt lgkmcnt(0)
	v_mfma_f32_32x32x16_bf16 v[4:19], v[40:43], v[88:91], v[4:19]
	ds_read_b128 v[36:39], v45 offset:128
	ds_read_b128 v[40:43], v45 offset:8320
	s_waitcnt lgkmcnt(1)
	v_mfma_f32_32x32x16_bf16 v[20:35], v[36:39], v[84:87], v[20:35]
	s_waitcnt lgkmcnt(0)
	v_mfma_f32_32x32x16_bf16 v[4:19], v[40:43], v[84:87], v[4:19]
	ds_read_b128 v[36:39], v46 offset:128
	ds_read_b128 v[40:43], v46 offset:8320
	s_waitcnt lgkmcnt(1)
	v_mfma_f32_32x32x16_bf16 v[20:35], v[36:39], v[80:83], v[20:35]
	s_waitcnt lgkmcnt(0)
	v_mfma_f32_32x32x16_bf16 v[4:19], v[40:43], v[80:83], v[4:19]
	ds_read_b128 v[36:39], v47 offset:128
	ds_read_b128 v[40:43], v47 offset:8320
	s_waitcnt lgkmcnt(1)
	v_mfma_f32_32x32x16_bf16 v[20:35], v[36:39], v[76:79], v[20:35]
	s_waitcnt lgkmcnt(0)
	v_mfma_f32_32x32x16_bf16 v[4:19], v[40:43], v[76:79], v[4:19]
	s_cbranch_scc1 .LBB0_626
; __device__ __forceinline__ void bias_mask_tile(f32x16& p0, f32x16& p1, int dq, const float* bt) {
;     const float NEG = -__builtin_inff();
; #pragma unroll
;     for (int r = 0; r < 16; ++r) {
;         const int c = (r & 3) + 8 * (r >> 2);
;         const int d0 = dq - c, d1 = dq - c - 32;
;         const unsigned i0 = (unsigned)d0 < 255u ? (unsigned)d0 : 255u, i1 = (unsigned)d1 < 255u ? (unsigned)d1 : 255u;
;         const float b0 = bt[i0], b1 = bt[i1];
;         p0[r] = d0 >= 0 ? p0[r] + b0 : NEG;
;         p1[r] = d1 >= 0 ? p1[r] + b1 : NEG;
;     }
; }
	v_or_b32_e32 v36, s85, v211
	v_or_b32_e32 v37, s84, v114
	v_sub_u32_e32 v76, v36, v37
	v_lshl_add_u32 v36, v76, 2, s64
	v_add_u32_e32 v36, 0xffffff14, v36
	ds_read_b32 v132, v36 offset:236
	ds_read_b32 v133, v36 offset:232
	ds_read_b32 v134, v36 offset:228
	ds_read_b32 v135, v36 offset:224
	ds_read_b32 v136, v36 offset:204
	ds_read_b32 v137, v36 offset:200
	ds_read_b32 v138, v36 offset:196
	ds_read_b32 v139, v36 offset:192
	ds_read_b32 v140, v36 offset:172
	ds_read_b32 v141, v36 offset:168
	ds_read_b32 v142, v36 offset:164
	ds_read_b32 v143, v36 offset:160
	ds_read_b32 v144, v36 offset:140
	ds_read_b32 v145, v36 offset:136
	ds_read_b32 v146, v36 offset:132
	v_cmp_lt_i32_e32 vcc, -1, v76
	v_cmp_lt_i32_e64 s[16:17], 0, v76
	s_waitcnt lgkmcnt(14)
	v_add_f32_e32 v20, v20, v132
	ds_read_b32 v147, v36 offset:128
	s_waitcnt lgkmcnt(14)
	v_add_f32_e32 v21, v21, v133
	ds_read_b32 v148, v36 offset:108
	v_cndmask_b32_e32 v20, v240, v20, vcc
	v_cndmask_b32_e64 v21, v240, v21, s[16:17]
	v_cmp_lt_i32_e32 vcc, 1, v76
	v_cmp_lt_i32_e64 s[16:17], 2, v76
	s_waitcnt lgkmcnt(14)
	v_add_f32_e32 v22, v22, v134
	ds_read_b32 v149, v36 offset:104
	s_waitcnt lgkmcnt(14)
	v_add_f32_e32 v23, v23, v135
	ds_read_b32 v150, v36 offset:100
	v_cndmask_b32_e32 v22, v240, v22, vcc
	v_cndmask_b32_e64 v23, v240, v23, s[16:17]
	v_cmp_lt_i32_e32 vcc, 7, v76
	v_cmp_lt_i32_e64 s[16:17], 8, v76
	s_waitcnt lgkmcnt(14)
	v_add_f32_e32 v24, v24, v136
	ds_read_b32 v151, v36 offset:96
	s_waitcnt lgkmcnt(14)
	v_add_f32_e32 v25, v25, v137
	ds_read_b32 v152, v36 offset:76
	v_cndmask_b32_e32 v24, v240, v24, vcc
	v_cndmask_b32_e64 v25, v240, v25, s[16:17]
	v_cmp_lt_i32_e32 vcc, 9, v76
	v_cmp_lt_i32_e64 s[16:17], 10, v76
	s_waitcnt lgkmcnt(14)
	v_add_f32_e32 v26, v26, v138
	ds_read_b32 v153, v36 offset:72
	s_waitcnt lgkmcnt(14)
	v_add_f32_e32 v27, v27, v139
	ds_read_b32 v154, v36 offset:68
	v_cndmask_b32_e32 v26, v240, v26, vcc
	v_cndmask_b32_e64 v27, v240, v27, s[16:17]
	v_cmp_lt_i32_e32 vcc, 15, v76
	v_cmp_lt_i32_e64 s[16:17], 16, v76
	s_waitcnt lgkmcnt(14)
	v_add_f32_e32 v28, v28, v140
	ds_read_b32 v155, v36 offset:64
	s_waitcnt lgkmcnt(14)
	v_add_f32_e32 v29, v29, v141
	ds_read_b32 v60, v36 offset:44
	v_cndmask_b32_e32 v28, v240, v28, vcc
	v_cndmask_b32_e64 v29, v240, v29, s[16:17]
	v_cmp_lt_i32_e32 vcc, 17, v76
	v_cmp_lt_i32_e64 s[16:17], 18, v76
	s_waitcnt lgkmcnt(14)
	v_add_f32_e32 v30, v30, v142
	ds_read_b32 v61, v36 offset:40
	s_waitcnt lgkmcnt(14)
	v_add_f32_e32 v31, v31, v143
	ds_read_b32 v62, v36 offset:36
	v_cndmask_b32_e32 v30, v240, v30, vcc
	v_cndmask_b32_e64 v31, v240, v31, s[16:17]
	v_cmp_lt_i32_e32 vcc, 23, v76
	v_cmp_lt_i32_e64 s[16:17], 24, v76
	s_waitcnt lgkmcnt(14)
	v_add_f32_e32 v32, v32, v144
	ds_read_b32 v63, v36 offset:32
	s_waitcnt lgkmcnt(14)
	v_add_f32_e32 v33, v33, v145
	ds_read_b32 v64, v36 offset:12
	v_cndmask_b32_e32 v32, v240, v32, vcc
	v_cndmask_b32_e64 v33, v240, v33, s[16:17]
	v_cmp_lt_i32_e32 vcc, 25, v76
	v_cmp_lt_i32_e64 s[16:17], 26, v76
	s_waitcnt lgkmcnt(14)
	v_add_f32_e32 v34, v34, v146
	ds_read_b32 v65, v36 offset:8
	s_waitcnt lgkmcnt(14)
	v_add_f32_e32 v35, v35, v147
	ds_read_b32 v66, v36 offset:4
	v_cndmask_b32_e32 v34, v240, v34, vcc
	v_cndmask_b32_e64 v35, v240, v35, s[16:17]
	v_cmp_lt_i32_e32 vcc, 31, v76
	v_cmp_lt_i32_e64 s[16:17], 32, v76
	s_waitcnt lgkmcnt(14)
	v_add_f32_e32 v4, v4, v148
	ds_read_b32 v67, v36 offset:0
	s_waitcnt lgkmcnt(14)
	v_add_f32_e32 v5, v5, v149
	v_cndmask_b32_e32 v4, v240, v4, vcc
	v_cndmask_b32_e64 v5, v240, v5, s[16:17]
	v_cmp_lt_i32_e32 vcc, 33, v76
	v_cmp_lt_i32_e64 s[16:17], 34, v76
	s_waitcnt lgkmcnt(13)
	v_add_f32_e32 v6, v6, v150
	s_waitcnt lgkmcnt(12)
	v_add_f32_e32 v7, v7, v151
	v_cndmask_b32_e32 v6, v240, v6, vcc
	v_cndmask_b32_e64 v7, v240, v7, s[16:17]
	v_cmp_lt_i32_e32 vcc, 39, v76
	v_cmp_lt_i32_e64 s[16:17], 40, v76
	s_waitcnt lgkmcnt(11)
	v_add_f32_e32 v8, v8, v152
	s_waitcnt lgkmcnt(10)
	v_add_f32_e32 v9, v9, v153
	v_cndmask_b32_e32 v8, v240, v8, vcc
	v_cndmask_b32_e64 v9, v240, v9, s[16:17]
	v_cmp_lt_i32_e32 vcc, 41, v76
	v_cmp_lt_i32_e64 s[16:17], 42, v76
	s_waitcnt lgkmcnt(9)
	v_add_f32_e32 v10, v10, v154
	s_waitcnt lgkmcnt(8)
	v_add_f32_e32 v11, v11, v155
	v_cndmask_b32_e32 v10, v240, v10, vcc
	v_cndmask_b32_e64 v11, v240, v11, s[16:17]
	v_cmp_lt_i32_e32 vcc, 47, v76
	v_cmp_lt_i32_e64 s[16:17], 48, v76
	s_waitcnt lgkmcnt(7)
	v_add_f32_e32 v12, v12, v60
	s_waitcnt lgkmcnt(6)
	v_add_f32_e32 v13, v13, v61
	v_cndmask_b32_e32 v12, v240, v12, vcc
	v_cndmask_b32_e64 v13, v240, v13, s[16:17]
	v_cmp_lt_i32_e32 vcc, 49, v76
	v_cmp_lt_i32_e64 s[16:17], 50, v76
	s_waitcnt lgkmcnt(5)
	v_add_f32_e32 v14, v14, v62
	s_waitcnt lgkmcnt(4)
	v_add_f32_e32 v15, v15, v63
	v_cndmask_b32_e32 v14, v240, v14, vcc
	v_cndmask_b32_e64 v15, v240, v15, s[16:17]
	v_cmp_lt_i32_e32 vcc, 55, v76
	v_cmp_lt_i32_e64 s[16:17], 56, v76
	s_waitcnt lgkmcnt(3)
	v_add_f32_e32 v16, v16, v64
	s_waitcnt lgkmcnt(2)
	v_add_f32_e32 v17, v17, v65
	v_cndmask_b32_e32 v16, v240, v16, vcc
	v_cndmask_b32_e64 v17, v240, v17, s[16:17]
	v_cmp_lt_i32_e32 vcc, 57, v76
	v_cmp_lt_i32_e64 s[16:17], 58, v76
	s_waitcnt lgkmcnt(1)
	v_add_f32_e32 v18, v18, v66
	s_waitcnt lgkmcnt(0)
	v_add_f32_e32 v19, v19, v67
	v_cndmask_b32_e32 v18, v240, v18, vcc
	v_cndmask_b32_e64 v19, v240, v19, s[16:17]

; #define A2_WRITET(buf) do { char* kd_ = lds + L_K + (buf) * SHM_K; char* vd_ = lds + L_V + (buf) * 2 * SHM_V; \
;         *(bf16x8*)(kd_ + kws) = sk0; *(bf16x8*)(kd_ + kws + 32 * 256) = sk1; *(bf16x8*)(vd_ + vst0) = sv00; *(bf16x8*)(vd_ + vst1) = sv01; *(bf16x8*)(vd_ + SHM_V + vst0) = sv10; *(bf16x8*)(vd_ + SHM_V + vst1) = sv11; } while (0)
; __device__ __forceinline__ void attn2_block(const Blk& c, char* lds) {
;     ...
;             __syncthreads();
;             if (s + 1 < NT) { asm volatile("s_waitcnt vmcnt(0)" ::: "memory"); A2_WRITET((s + 1) & 1); }
;             __syncthreads();
;         }
;         if (hi == 0) LBb[r32] = l_reg;
;         __syncthreads();
.LBB0_630:
	s_or_b64 exec, exec, s[16:17]
	s_waitcnt lgkmcnt(0)
	s_waitcnt vmcnt(0)
	s_barrier
	s_barrier
	s_and_saveexec_b64 s[4:5], s[2:3]
	s_cbranch_execz .LBB0_538
	v_add_f32_e32 v2, v4, v5
	v_fmac_f32_e32 v2, v115, v36
	v_lshl_add_u32 v4, v211, 2, s65
	ds_write_b32 v4, v2
	s_branch .LBB0_538

; __global__ void __launch_bounds__(NTHR, 2) mega_fwd(Args a) {
	.amdhsa_kernel _Z8mega_fwd4Args
		.amdhsa_group_segment_fixed_size 0
		.amdhsa_private_segment_fixed_size 0
		.amdhsa_kernarg_size 464
		.amdhsa_user_sgpr_count 2
		.amdhsa_user_sgpr_dispatch_ptr 0
		.amdhsa_user_sgpr_queue_ptr 0
		.amdhsa_user_sgpr_kernarg_segment_ptr 1
		.amdhsa_user_sgpr_dispatch_id 0
		.amdhsa_user_sgpr_kernarg_preload_length 0
		.amdhsa_user_sgpr_kernarg_preload_offset 0
		.amdhsa_user_sgpr_private_segment_size 0
		.amdhsa_uses_dynamic_stack 0
		.amdhsa_enable_private_segment 0
		.amdhsa_system_sgpr_workgroup_id_x 1
		.amdhsa_system_sgpr_workgroup_id_y 0
		.amdhsa_system_sgpr_workgroup_id_z 0
		.amdhsa_system_sgpr_workgroup_info 0
		.amdhsa_system_vgpr_workitem_id 2
		.amdhsa_next_free_vgpr 256
		.amdhsa_next_free_sgpr 102
		.amdhsa_accum_offset 256
		.amdhsa_reserve_vcc 1
		.amdhsa_float_round_mode_32 0
		.amdhsa_float_round_mode_16_64 0
		.amdhsa_float_denorm_mode_32 3
		.amdhsa_float_denorm_mode_16_64 3
		.amdhsa_dx10_clamp 1
		.amdhsa_ieee_mode 1
		.amdhsa_fp16_overflow 0
		.amdhsa_tg_split 0
		.amdhsa_exception_fp_ieee_invalid_op 0
		.amdhsa_exception_fp_denorm_src 0
		.amdhsa_exception_fp_ieee_div_zero 0
		.amdhsa_exception_fp_ieee_overflow 0
		.amdhsa_exception_fp_ieee_underflow 0
		.amdhsa_exception_fp_ieee_inexact 0
		.amdhsa_exception_int_div_zero 0
	.end_amdhsa_kernel

; __global__ void __launch_bounds__(NTHR, 2) mega_fwd(Args a) {
amdhsa.kernels:
  - .agpr_count:     0
    .args:
      - .offset:         0
        .size:           208
        .value_kind:     by_value
      - .offset:         208
        .size:           4
        .value_kind:     hidden_block_count_x
      - .offset:         212
        .size:           4
        .value_kind:     hidden_block_count_y
      - .offset:         216
        .size:           4
        .value_kind:     hidden_block_count_z
      - .offset:         220
        .size:           2
        .value_kind:     hidden_group_size_x
      - .offset:         222
        .size:           2
        .value_kind:     hidden_group_size_y
      - .offset:         224
        .size:           2
        .value_kind:     hidden_group_size_z
      - .offset:         226
        .size:           2
        .value_kind:     hidden_remainder_x
      - .offset:         228
        .size:           2
        .value_kind:     hidden_remainder_y
      - .offset:         230
        .size:           2
        .value_kind:     hidden_remainder_z
      - .offset:         248
        .size:           8
        .value_kind:     hidden_global_offset_x
      - .offset:         256
        .size:           8
        .value_kind:     hidden_global_offset_y
      - .offset:         264
        .size:           8
        .value_kind:     hidden_global_offset_z
      - .offset:         272
        .size:           2
        .value_kind:     hidden_grid_dims
      - .offset:         296
        .size:           8
        .value_kind:     hidden_multigrid_sync_arg
      - .offset:         328
        .size:           4
        .value_kind:     hidden_dynamic_lds_size
    .group_segment_fixed_size: 0
    .kernarg_segment_align: 8
    .kernarg_segment_size: 464
    .language:       OpenCL C
    .language_version:
      - 2
      - 0
    .max_flat_workgroup_size: 512
    .name:           _Z8mega_fwd4Args
    .private_segment_fixed_size: 0
    .sgpr_count:     108
    .sgpr_spill_count: 68
    .symbol:         _Z8mega_fwd4Args.kd
    .uniform_work_group_size: 1
    .uses_dynamic_stack: false
    .vgpr_count:     256
    .vgpr_spill_count: 0
    .wavefront_size: 64
